# p17 + O1 tile groups 4 row-tiles x 16 col-tiles (XCD round 4x8 instead of 8x4)
# baseline (speedup 1.0000x reference)
.LBB0_156:
	s_andn2_b64 vcc, exec, s[0:1]
	s_cbranch_vccnz .LBB0_239
	v_readlane_b32 s0, v254, 0
	v_readlane_b32 s1, v254, 1
	v_readlane_b32 s2, v254, 4
	s_mov_b32 s20, s80
	s_waitcnt vmcnt(0)
	v_mov_b64_e32 v[2:3], s[0:1]
	v_mbcnt_lo_u32_b32 v0, -1, 0
	v_mbcnt_hi_u32_b32 v0, -1, v0
	flat_load_dwordx2 v[142:143], v[2:3] offset:224
	v_mbcnt_lo_u32_b32 v0, -1, 0
	v_mbcnt_hi_u32_b32 v0, -1, v0
	s_cmpk_lt_i32 s20, 0xa00
	v_add_u32_e32 v0, s81, v0
	s_cselect_b64 s[2:3], -1, 0
	s_cmpk_gt_i32 s20, 0x9ff
	v_readfirstlane_b32 s6, v0
	s_cbranch_scc1 .LBB0_159
	s_ashr_i32 s0, s20, 31
	s_lshr_b32 s0, s0, 29
	s_add_i32 s0, s20, s0
	s_ashr_i32 s1, s0, 3
	s_and_b32 s0, s0, -8
	s_sub_i32 s0, s20, s0
	s_cmp_lt_i32 s0, 0
	s_movk_i32 s7, 0x141
	s_cselect_b32 s7, s7, 0x140
	s_mul_i32 s0, s0, s7
	s_add_i32 s0, s0, s1
	s_ashr_i32 s1, s0, 31
	s_lshr_b32 s1, s1, 26
	s_add_i32 s1, s0, s1
	s_ashr_i32 s7, s1, 6
	s_and_b32 s1, s1, 0xffc0
	s_sub_i32 s0, s0, s1
	s_bfe_i32 s1, s0, 0x80000
	s_bfe_u32 s1, s1, 0x3000c
	s_add_i32 s1, s0, s1
	s_bfe_i32 s8, s1, 0x80000
	s_and_b32 s1, s1, 0xfc
	s_sub_i32 s0, s0, s1
	s_lshl_b32 s7, s7, 2
	s_sext_i32_i16 s8, s8
	s_sext_i32_i8 s0, s0
	s_add_i32 s0, s7, s0
	s_ashr_i32 s12, s8, 2

.LBB0_165:
	s_add_i32 s31, s31, 1
	s_mul_i32 s1, s31, s29
	s_mul_hi_u32 s2, s31, s21
	s_add_i32 s1, s2, s1
	s_mul_i32 s2, s31, s21
	s_add_u32 s2, s2, s20
	s_addc_u32 s3, s1, s30
	v_mov_b64_e32 v[146:147], 0xa00
	v_cmp_lt_i64_e64 s[8:9], s[2:3], v[146:147]
	v_mov_b64_e32 v[146:147], 0x9ff
	v_cmp_gt_i64_e32 vcc, s[2:3], v[146:147]
	s_cbranch_vccnz .LBB0_167
	s_ashr_i32 s1, s2, 31
	s_lshr_b32 s1, s1, 29
	s_add_i32 s1, s2, s1
	s_ashr_i32 s3, s1, 3
	s_and_b32 s1, s1, -8
	s_sub_i32 s1, s2, s1
	s_cmp_lt_i32 s1, 0
	s_movk_i32 s2, 0x141
	s_cselect_b32 s2, s2, 0x140
	s_mul_i32 s1, s1, s2
	s_add_i32 s1, s1, s3
	s_ashr_i32 s2, s1, 31
	s_lshr_b32 s2, s2, 26
	s_add_i32 s2, s1, s2
	s_ashr_i32 s3, s2, 6
	s_lshl_b32 s3, s3, 2
	s_and_b32 s2, s2, 0xffffffc0
	s_sub_i32 s1, s1, s2
	s_lshr_b32 s16, s1, 2
	s_and_b32 s1, s1, 3
	s_add_i32 s18, s3, s1
